# union version with the prep weight-copy ranges rebalanced 10/2/9 (mod-item blocks / bias blocks / the rest) after timing both halves
# baseline (speedup 1.0000x reference)
.LBB0_583:
	v_readlane_b32 s0, v253, 12
	v_readlane_b32 s1, v253, 13
	s_andn2_b64 vcc, exec, s[0:1]
	s_waitcnt lgkmcnt(0)
	s_barrier
	s_cbranch_vccnz .LBB0_639
	v_lshlrev_b32_e32 v0, 3, v16
	v_bfe_u32 v4, v16, 3, 3
	v_and_b32_e32 v0, 56, v0
	v_and_b32_e32 v2, 31, v16
	v_bfe_u32 v3, v16, 5, 1
	v_mul_u32_u24_e32 v1, 0x84, v0
	v_lshlrev_b32_e32 v5, 2, v4
	v_readlane_b32 s0, v253, 30
	s_add_u32 s2, s2, 0x800000
	v_lshlrev_b32_e32 v9, 2, v2
	v_add3_u32 v5, s0, v1, v5
	v_mul_u32_u24_e32 v1, 0x84, v3
	s_addc_u32 s18, s11, 0
	v_or_b32_e32 v6, 8, v4
	v_or_b32_e32 v7, 16, v4
	v_or_b32_e32 v8, 24, v4
	v_add3_u32 v9, v1, v9, s0
	v_lshlrev_b32_e32 v160, 1, v0
	v_readlane_b32 s19, v254, 47
	v_readlane_b32 s12, v252, 23
	v_readlane_b32 s0, v252, 20
	s_nop 3
	s_cmp_lt_u32 s0, 96
	s_cbranch_scc1 .Lw3_lo
	s_cmp_lt_u32 s0, 100
	s_cbranch_scc1 .Lw3_mid
	s_sub_i32 s19, s19, 800
	s_mul_i32 s19, s19, 9
	s_add_i32 s19, s19, 7744
	s_add_i32 s0, s19, 9
	s_branch .Lw3_set
.Lw3_mid:
	s_sub_i32 s19, s19, 768
	s_lshl_b32 s19, s19, 1
	s_add_i32 s19, s19, 7680
	s_add_i32 s0, s19, 2
	s_branch .Lw3_set
.Lw3_lo:
	s_mul_i32 s19, s19, 10
	s_add_i32 s0, s19, 10
